# version 93 plus residual-GEMM epilogue: counted vmcnt waits at each residual load's first consumer instead of one vmcnt(0) after all sixteen loads
# speedup vs baseline: 1.0090x; 1.0090x over previous
; __device__ __forceinline__ unsigned cvt_pk_bf16(float lo, float hi) { unsigned r; asm volatile("v_cvt_pk_bf16_f32 %0, %1, %2" : "=v"(r) : "v"(lo), "v"(hi)); return r; }
;     __device__ __forceinline__ void operator()(const f32x4 (&acc)[2][2][4][2], const Unit& u, int wr, int wc, int fr, int fq) const {
;     ...
; #pragma unroll
;         for (int ai = 0; ai < 2; ++ai)
; #pragma unroll
;             for (int m = 0; m < 4; ++m)
; #pragma unroll
;                 for (int bj = 0; bj < 2; ++bj) xv[ai][m][bj] = *(const u32x4*)(xb + (size_t)(row0 + ai * HALF + m * 16) * 1024 + col0 + bj * HALF);
;         float ssv[2][4];
; #pragma unroll
;         for (int ai = 0; ai < 2; ++ai)
; #pragma unroll
;             for (int m = 0; m < 4; ++m) {
;                 const int row = row0 + ai * HALF + m * 16;
;                 float ss = 0.f;
; #pragma unroll
;                 for (int bj = 0; bj < 2; ++bj) {
;                     const u32x4 xo = xv[ai][m][bj]; u32x4 w;
; #pragma unroll
;                     for (int k = 0; k < 4; ++k) {
;                         const float a0 = __uint_as_float(xo[k] << 16) + acc[ai][bj][m][k >> 1][(k & 1) * 2] * scale, a1 = __uint_as_float(xo[k] & 0xffff0000u) + acc[ai][bj][m][k >> 1][(k & 1) * 2 + 1] * scale;
;                         const unsigned p = cvt_pk_bf16(a0, a1); w[k] = p;
;                         const float r0 = __uint_as_float(p << 16), r1 = __uint_as_float(p & 0xffff0000u); ss += r0 * r0 + r1 * r1;
;                     }
;                     *(u32x4*)(xb + (size_t)row * 1024 + col0 + bj * HALF) = w;
.LBB0_180:
	v_lshl_or_b32 v126, s49, 8, v248
	v_lshl_add_u32 v210, s50, 8, v246
	v_ashrrev_i32_e32 v127, 31, v126
	v_lshlrev_b64 v[212:213], 1, v[126:127]
	v_ashrrev_i32_e32 v211, 31, v210
	v_lshl_add_u64 v[126:127], s[84:85], 0, v[212:213]
	v_lshlrev_b64 v[228:229], 11, v[210:211]
	v_lshl_add_u64 v[128:129], v[126:127], 0, v[228:229]
	global_load_dwordx4 v[238:241], v[128:129], off
	global_load_dwordx4 v[190:193], v[128:129], off offset:256
	v_or_b32_e32 v128, 16, v210
	v_ashrrev_i32_e32 v129, 31, v128
	v_lshlrev_b64 v[226:227], 11, v[128:129]
	v_lshl_add_u64 v[128:129], v[126:127], 0, v[226:227]
	global_load_dwordx4 v[186:189], v[128:129], off
	global_load_dwordx4 v[182:185], v[128:129], off offset:256
	v_or_b32_e32 v128, 32, v210
	v_ashrrev_i32_e32 v129, 31, v128
	v_lshlrev_b64 v[224:225], 11, v[128:129]
	v_lshl_add_u64 v[128:129], v[126:127], 0, v[224:225]
	global_load_dwordx4 v[178:181], v[128:129], off
	global_load_dwordx4 v[170:173], v[128:129], off offset:256
	v_or_b32_e32 v128, 48, v210
	v_ashrrev_i32_e32 v129, 31, v128
	s_mov_b64 s[10:11], 0x40000
	v_lshlrev_b64 v[222:223], 11, v[128:129]
	v_lshl_add_u64 v[220:221], v[228:229], 0, s[10:11]
	s_mov_b64 s[10:11], 0x48000
	v_lshl_add_u64 v[128:129], v[126:127], 0, v[222:223]
	v_lshl_add_u64 v[218:219], v[228:229], 0, s[10:11]
	s_mov_b64 s[10:11], 0x50000
	global_load_dwordx4 v[162:165], v[128:129], off
	global_load_dwordx4 v[154:157], v[128:129], off offset:256
	v_lshl_add_u64 v[128:129], v[126:127], 0, v[220:221]
	v_lshl_add_u64 v[216:217], v[228:229], 0, s[10:11]
	s_mov_b64 s[10:11], 0x58000
	global_load_dwordx4 v[158:161], v[128:129], off
	global_load_dwordx4 v[150:153], v[128:129], off offset:256
	v_lshl_add_u64 v[128:129], v[126:127], 0, v[218:219]
	v_lshl_add_u64 v[214:215], v[228:229], 0, s[10:11]
	global_load_dwordx4 v[146:149], v[128:129], off
	global_load_dwordx4 v[142:145], v[128:129], off offset:256
	v_lshl_add_u64 v[128:129], v[126:127], 0, v[216:217]
	v_lshl_add_u64 v[126:127], v[126:127], 0, v[214:215]
	global_load_dwordx4 v[138:141], v[128:129], off
	global_load_dwordx4 v[134:137], v[128:129], off offset:256
	global_load_dwordx4 v[130:133], v[126:127], off
	s_nop 0
	global_load_dwordx4 v[126:129], v[126:127], off offset:256
	s_waitcnt vmcnt(15)
	v_lshlrev_b32_e32 v250, 16, v238
	v_fmac_f32_e32 v250, v2, v174
	v_and_b32_e32 v174, 0xffff0000, v238
	v_fmac_f32_e32 v174, v2, v175
	v_cvt_pk_bf16_f32 v174, v250, v174
	s_nop 0
	v_and_b32_e32 v238, 0xffff0000, v174
	v_lshlrev_b32_e32 v175, 16, v174
	v_mul_f32_e32 v238, v238, v238
	v_fmac_f32_e32 v238, v175, v175
	v_lshlrev_b32_e32 v175, 16, v239
	v_fmac_f32_e32 v175, v2, v176
	v_and_b32_e32 v176, 0xffff0000, v239
	v_fmac_f32_e32 v176, v2, v177
	v_cvt_pk_bf16_f32 v175, v175, v176
	s_nop 0
	v_and_b32_e32 v177, 0xffff0000, v175
	v_lshlrev_b32_e32 v176, 16, v175
	v_mul_f32_e32 v177, v177, v177
	v_fmac_f32_e32 v177, v176, v176
	v_lshlrev_b32_e32 v176, 16, v240
	v_fmac_f32_e32 v176, v2, v166
	v_and_b32_e32 v166, 0xffff0000, v240
	v_fmac_f32_e32 v166, v2, v167
	v_cvt_pk_bf16_f32 v176, v176, v166
	v_add_f32_e32 v177, v238, v177
	v_and_b32_e32 v167, 0xffff0000, v176
	v_lshlrev_b32_e32 v166, 16, v176
	v_mul_f32_e32 v167, v167, v167
	v_fmac_f32_e32 v167, v166, v166
	v_add_f32_e32 v166, v177, v167
	v_lshlrev_b32_e32 v167, 16, v241
	v_fmac_f32_e32 v167, v2, v168
	v_and_b32_e32 v168, 0xffff0000, v241
	v_fmac_f32_e32 v168, v2, v169
	v_cvt_pk_bf16_f32 v177, v167, v168
	s_waitcnt vmcnt(14)
	v_lshlrev_b32_e32 v169, 16, v190
	v_and_b32_e32 v168, 0xffff0000, v177
	v_lshlrev_b32_e32 v167, 16, v177
	v_mul_f32_e32 v168, v168, v168
	v_fmac_f32_e32 v168, v167, v167
	v_add_f32_e32 v168, v166, v168
	v_lshl_add_u64 v[166:167], s[84:85], 0, v[228:229]
	v_fmac_f32_e32 v169, v2, v122
	v_and_b32_e32 v122, 0xffff0000, v190
	v_lshl_add_u64 v[166:167], v[166:167], 0, v[212:213]
	v_fmac_f32_e32 v122, v2, v123
	global_store_dwordx4 v[166:167], v[174:177], off
	v_cvt_pk_bf16_f32 v122, v169, v122
	s_nop 0
	v_and_b32_e32 v169, 0xffff0000, v122
	v_lshlrev_b32_e32 v123, 16, v122
	v_mul_f32_e32 v169, v169, v169
	v_fmac_f32_e32 v169, v123, v123
	v_lshlrev_b32_e32 v123, 16, v191
	v_fmac_f32_e32 v123, v2, v124
	v_and_b32_e32 v124, 0xffff0000, v191
	v_fmac_f32_e32 v124, v2, v125
	v_cvt_pk_bf16_f32 v123, v123, v124
	v_add_f32_e32 v168, v168, v169
	v_and_b32_e32 v125, 0xffff0000, v123
	v_lshlrev_b32_e32 v124, 16, v123
	v_mul_f32_e32 v125, v125, v125
	v_fmac_f32_e32 v125, v124, v124
	v_lshlrev_b32_e32 v124, 16, v192
	v_fmac_f32_e32 v124, v2, v118
	v_and_b32_e32 v118, 0xffff0000, v192
	v_fmac_f32_e32 v118, v2, v119
	v_cvt_pk_bf16_f32 v124, v124, v118
	v_add_f32_e32 v125, v168, v125
	v_and_b32_e32 v119, 0xffff0000, v124
	v_lshlrev_b32_e32 v118, 16, v124
	v_mul_f32_e32 v119, v119, v119
	v_fmac_f32_e32 v119, v118, v118
	v_add_f32_e32 v118, v125, v119
	v_lshlrev_b32_e32 v119, 16, v193
	v_fmac_f32_e32 v119, v2, v120
	v_and_b32_e32 v120, 0xffff0000, v193
	v_fmac_f32_e32 v120, v2, v121
	v_cvt_pk_bf16_f32 v125, v119, v120
	global_store_dwordx4 v[166:167], v[122:125], off offset:256
	v_and_b32_e32 v120, 0xffff0000, v125
	v_lshlrev_b32_e32 v119, 16, v125
	v_mul_f32_e32 v120, v120, v120
	v_fmac_f32_e32 v120, v119, v119
	s_waitcnt vmcnt(15)
; __device__ __forceinline__ unsigned cvt_pk_bf16(float lo, float hi) { unsigned r; asm volatile("v_cvt_pk_bf16_f32 %0, %1, %2" : "=v"(r) : "v"(lo), "v"(hi)); return r; }
;     __device__ __forceinline__ void operator()(const f32x4 (&acc)[2][2][4][2], const Unit& u, int wr, int wc, int fr, int fq) const {
;     ...
;             for (int m = 0; m < 4; ++m) {
;                 const int row = row0 + ai * HALF + m * 16;
;                 float ss = 0.f;
; #pragma unroll
;                 for (int bj = 0; bj < 2; ++bj) {
;                     const u32x4 xo = xv[ai][m][bj]; u32x4 w;
; #pragma unroll
;                     for (int k = 0; k < 4; ++k) {
;                         const float a0 = __uint_as_float(xo[k] << 16) + acc[ai][bj][m][k >> 1][(k & 1) * 2] * scale, a1 = __uint_as_float(xo[k] & 0xffff0000u) + acc[ai][bj][m][k >> 1][(k & 1) * 2 + 1] * scale;
;                         const unsigned p = cvt_pk_bf16(a0, a1); w[k] = p;
;                         const float r0 = __uint_as_float(p << 16), r1 = __uint_as_float(p & 0xffff0000u); ss += r0 * r0 + r1 * r1;
;                     }
;                     *(u32x4*)(xb + (size_t)row * 1024 + col0 + bj * HALF) = w;
	v_lshlrev_b32_e32 v119, 16, v186
	v_fmac_f32_e32 v119, v2, v114
	v_and_b32_e32 v114, 0xffff0000, v186
	v_fmac_f32_e32 v114, v2, v115
	v_cvt_pk_bf16_f32 v114, v119, v114
	v_add_f32_e32 v118, v118, v120
	v_and_b32_e32 v119, 0xffff0000, v114
	v_lshlrev_b32_e32 v115, 16, v114
	v_mul_f32_e32 v119, v119, v119
	v_fmac_f32_e32 v119, v115, v115
	v_lshlrev_b32_e32 v115, 16, v187
	v_fmac_f32_e32 v115, v2, v116
	v_and_b32_e32 v116, 0xffff0000, v187
	v_fmac_f32_e32 v116, v2, v117
	v_cvt_pk_bf16_f32 v115, v115, v116
	s_nop 0
	v_and_b32_e32 v117, 0xffff0000, v115
	v_lshlrev_b32_e32 v116, 16, v115
	v_mul_f32_e32 v117, v117, v117
	v_fmac_f32_e32 v117, v116, v116
	v_lshlrev_b32_e32 v116, 16, v188
	v_fmac_f32_e32 v116, v2, v110
	v_and_b32_e32 v110, 0xffff0000, v188
	v_fmac_f32_e32 v110, v2, v111
	v_cvt_pk_bf16_f32 v116, v116, v110
	v_add_f32_e32 v117, v119, v117
	v_and_b32_e32 v111, 0xffff0000, v116
	v_lshlrev_b32_e32 v110, 16, v116
	v_mul_f32_e32 v111, v111, v111
	v_fmac_f32_e32 v111, v110, v110
	v_add_f32_e32 v110, v117, v111
	v_lshlrev_b32_e32 v111, 16, v189
	v_fmac_f32_e32 v111, v2, v112
	v_and_b32_e32 v112, 0xffff0000, v189
	v_fmac_f32_e32 v112, v2, v113
	v_cvt_pk_bf16_f32 v117, v111, v112
	s_waitcnt vmcnt(14)
	v_lshlrev_b32_e32 v113, 16, v182
	v_and_b32_e32 v112, 0xffff0000, v117
	v_lshlrev_b32_e32 v111, 16, v117
	v_mul_f32_e32 v112, v112, v112
	v_fmac_f32_e32 v112, v111, v111
	v_add_f32_e32 v112, v110, v112
	v_lshl_add_u64 v[110:111], s[84:85], 0, v[226:227]
	v_fmac_f32_e32 v113, v2, v106
	v_and_b32_e32 v106, 0xffff0000, v182
	v_lshl_add_u64 v[110:111], v[110:111], 0, v[212:213]
	v_fmac_f32_e32 v106, v2, v107
	global_store_dwordx4 v[110:111], v[114:117], off
	v_cvt_pk_bf16_f32 v106, v113, v106
	s_nop 0
	v_and_b32_e32 v113, 0xffff0000, v106
	v_lshlrev_b32_e32 v107, 16, v106
	v_mul_f32_e32 v113, v113, v113
	v_fmac_f32_e32 v113, v107, v107
	v_lshlrev_b32_e32 v107, 16, v183
	v_fmac_f32_e32 v107, v2, v108
	v_and_b32_e32 v108, 0xffff0000, v183
	v_fmac_f32_e32 v108, v2, v109
	v_cvt_pk_bf16_f32 v107, v107, v108
	v_add_f32_e32 v112, v112, v113
	v_and_b32_e32 v109, 0xffff0000, v107
	v_lshlrev_b32_e32 v108, 16, v107
	v_mul_f32_e32 v109, v109, v109
	v_fmac_f32_e32 v109, v108, v108
	v_lshlrev_b32_e32 v108, 16, v184
	v_fmac_f32_e32 v108, v2, v102
	v_and_b32_e32 v102, 0xffff0000, v184
	v_fmac_f32_e32 v102, v2, v103
	v_cvt_pk_bf16_f32 v108, v108, v102
	v_add_f32_e32 v109, v112, v109
	v_and_b32_e32 v103, 0xffff0000, v108
	v_lshlrev_b32_e32 v102, 16, v108
	v_mul_f32_e32 v103, v103, v103
	v_fmac_f32_e32 v103, v102, v102
	v_add_f32_e32 v102, v109, v103
	v_lshlrev_b32_e32 v103, 16, v185
	v_fmac_f32_e32 v103, v2, v104
	v_and_b32_e32 v104, 0xffff0000, v185
	v_fmac_f32_e32 v104, v2, v105
	v_cvt_pk_bf16_f32 v109, v103, v104
	global_store_dwordx4 v[110:111], v[106:109], off offset:256
	v_and_b32_e32 v104, 0xffff0000, v109
	v_lshlrev_b32_e32 v103, 16, v109
	v_mul_f32_e32 v104, v104, v104
	v_fmac_f32_e32 v104, v103, v103
	s_waitcnt vmcnt(15)
	v_lshlrev_b32_e32 v103, 16, v178
	v_fmac_f32_e32 v103, v2, v98
	v_and_b32_e32 v98, 0xffff0000, v178
	v_fmac_f32_e32 v98, v2, v99
	v_cvt_pk_bf16_f32 v98, v103, v98
	v_add_f32_e32 v102, v102, v104
	v_and_b32_e32 v103, 0xffff0000, v98
	v_lshlrev_b32_e32 v99, 16, v98
	v_mul_f32_e32 v103, v103, v103
	v_fmac_f32_e32 v103, v99, v99
	v_lshlrev_b32_e32 v99, 16, v179
	v_fmac_f32_e32 v99, v2, v100
	v_and_b32_e32 v100, 0xffff0000, v179
	v_fmac_f32_e32 v100, v2, v101
	v_cvt_pk_bf16_f32 v99, v99, v100
	s_nop 0
	v_and_b32_e32 v101, 0xffff0000, v99
	v_lshlrev_b32_e32 v100, 16, v99
	v_mul_f32_e32 v101, v101, v101
	v_fmac_f32_e32 v101, v100, v100
	v_lshlrev_b32_e32 v100, 16, v180
	v_fmac_f32_e32 v100, v2, v94
	v_and_b32_e32 v94, 0xffff0000, v180
	v_fmac_f32_e32 v94, v2, v95
	v_cvt_pk_bf16_f32 v100, v100, v94
	v_add_f32_e32 v101, v103, v101
	v_and_b32_e32 v95, 0xffff0000, v100
	v_lshlrev_b32_e32 v94, 16, v100
	v_mul_f32_e32 v95, v95, v95
	v_fmac_f32_e32 v95, v94, v94
	v_add_f32_e32 v94, v101, v95
	v_lshlrev_b32_e32 v95, 16, v181
	v_fmac_f32_e32 v95, v2, v96
	v_and_b32_e32 v96, 0xffff0000, v181
	v_fmac_f32_e32 v96, v2, v97
	v_cvt_pk_bf16_f32 v101, v95, v96
	s_waitcnt vmcnt(14)
	v_lshlrev_b32_e32 v97, 16, v170
	v_and_b32_e32 v96, 0xffff0000, v101
	v_lshlrev_b32_e32 v95, 16, v101
	v_mul_f32_e32 v96, v96, v96
	v_fmac_f32_e32 v96, v95, v95
	v_add_f32_e32 v96, v94, v96
	v_lshl_add_u64 v[94:95], s[84:85], 0, v[224:225]
	v_fmac_f32_e32 v97, v2, v90
	v_and_b32_e32 v90, 0xffff0000, v170
	v_lshl_add_u64 v[94:95], v[94:95], 0, v[212:213]
	v_fmac_f32_e32 v90, v2, v91
	global_store_dwordx4 v[94:95], v[98:101], off
	v_cvt_pk_bf16_f32 v90, v97, v90
	s_nop 0
	v_and_b32_e32 v97, 0xffff0000, v90
	v_lshlrev_b32_e32 v91, 16, v90
	v_mul_f32_e32 v97, v97, v97
	v_fmac_f32_e32 v97, v91, v91
	v_lshlrev_b32_e32 v91, 16, v171
	v_fmac_f32_e32 v91, v2, v92
	v_and_b32_e32 v92, 0xffff0000, v171
	v_fmac_f32_e32 v92, v2, v93
	v_cvt_pk_bf16_f32 v91, v91, v92
	v_add_f32_e32 v96, v96, v97
	v_and_b32_e32 v93, 0xffff0000, v91
	v_lshlrev_b32_e32 v92, 16, v91
	v_mul_f32_e32 v93, v93, v93
	v_fmac_f32_e32 v93, v92, v92
	v_lshlrev_b32_e32 v92, 16, v172
	v_fmac_f32_e32 v92, v2, v86
	v_and_b32_e32 v86, 0xffff0000, v172
	v_fmac_f32_e32 v86, v2, v87
	v_cvt_pk_bf16_f32 v92, v92, v86
	v_add_f32_e32 v93, v96, v93
	v_and_b32_e32 v87, 0xffff0000, v92
	v_lshlrev_b32_e32 v86, 16, v92
	v_mul_f32_e32 v87, v87, v87
	v_fmac_f32_e32 v87, v86, v86
	v_add_f32_e32 v86, v93, v87
	v_lshlrev_b32_e32 v87, 16, v173
	v_fmac_f32_e32 v87, v2, v88
	v_and_b32_e32 v88, 0xffff0000, v173
	v_fmac_f32_e32 v88, v2, v89
	v_cvt_pk_bf16_f32 v93, v87, v88
	global_store_dwordx4 v[94:95], v[90:93], off offset:256
	v_and_b32_e32 v88, 0xffff0000, v93
	v_lshlrev_b32_e32 v87, 16, v93
	v_mul_f32_e32 v88, v88, v88
	v_fmac_f32_e32 v88, v87, v87
	s_waitcnt vmcnt(15)
; __device__ __forceinline__ unsigned cvt_pk_bf16(float lo, float hi) { unsigned r; asm volatile("v_cvt_pk_bf16_f32 %0, %1, %2" : "=v"(r) : "v"(lo), "v"(hi)); return r; }
;     __device__ __forceinline__ void operator()(const f32x4 (&acc)[2][2][4][2], const Unit& u, int wr, int wc, int fr, int fq) const {
;     ...
;             for (int m = 0; m < 4; ++m) {
;                 const int row = row0 + ai * HALF + m * 16;
;                 float ss = 0.f;
; #pragma unroll
;                 for (int bj = 0; bj < 2; ++bj) {
;                     const u32x4 xo = xv[ai][m][bj]; u32x4 w;
; #pragma unroll
;                     for (int k = 0; k < 4; ++k) {
;                         const float a0 = __uint_as_float(xo[k] << 16) + acc[ai][bj][m][k >> 1][(k & 1) * 2] * scale, a1 = __uint_as_float(xo[k] & 0xffff0000u) + acc[ai][bj][m][k >> 1][(k & 1) * 2 + 1] * scale;
;                         const unsigned p = cvt_pk_bf16(a0, a1); w[k] = p;
;                         const float r0 = __uint_as_float(p << 16), r1 = __uint_as_float(p & 0xffff0000u); ss += r0 * r0 + r1 * r1;
;                     }
;                     *(u32x4*)(xb + (size_t)row * 1024 + col0 + bj * HALF) = w;
	v_lshlrev_b32_e32 v87, 16, v162
	v_fmac_f32_e32 v87, v2, v82
	v_and_b32_e32 v82, 0xffff0000, v162
	v_fmac_f32_e32 v82, v2, v83
	v_cvt_pk_bf16_f32 v82, v87, v82
	v_add_f32_e32 v86, v86, v88
	v_and_b32_e32 v87, 0xffff0000, v82
	v_lshlrev_b32_e32 v83, 16, v82
	v_mul_f32_e32 v87, v87, v87
	v_fmac_f32_e32 v87, v83, v83
	v_lshlrev_b32_e32 v83, 16, v163
	v_fmac_f32_e32 v83, v2, v84
	v_and_b32_e32 v84, 0xffff0000, v163
	v_fmac_f32_e32 v84, v2, v85
	v_cvt_pk_bf16_f32 v83, v83, v84
	s_nop 0
	v_and_b32_e32 v85, 0xffff0000, v83
	v_lshlrev_b32_e32 v84, 16, v83
	v_mul_f32_e32 v85, v85, v85
	v_fmac_f32_e32 v85, v84, v84
	v_lshlrev_b32_e32 v84, 16, v164
	v_fmac_f32_e32 v84, v2, v78
	v_and_b32_e32 v78, 0xffff0000, v164
	v_fmac_f32_e32 v78, v2, v79
	v_cvt_pk_bf16_f32 v84, v84, v78
	v_add_f32_e32 v85, v87, v85
	v_and_b32_e32 v79, 0xffff0000, v84
	v_lshlrev_b32_e32 v78, 16, v84
	v_mul_f32_e32 v79, v79, v79
	v_fmac_f32_e32 v79, v78, v78
	v_add_f32_e32 v78, v85, v79
	v_lshlrev_b32_e32 v79, 16, v165
	v_fmac_f32_e32 v79, v2, v80
	v_and_b32_e32 v80, 0xffff0000, v165
	v_fmac_f32_e32 v80, v2, v81
	v_cvt_pk_bf16_f32 v85, v79, v80
	s_waitcnt vmcnt(14)
	v_lshlrev_b32_e32 v81, 16, v154
	v_and_b32_e32 v80, 0xffff0000, v85
	v_lshlrev_b32_e32 v79, 16, v85
	v_mul_f32_e32 v80, v80, v80
	v_fmac_f32_e32 v80, v79, v79
	v_add_f32_e32 v80, v78, v80
	v_lshl_add_u64 v[78:79], s[84:85], 0, v[222:223]
	v_fmac_f32_e32 v81, v2, v74
	v_and_b32_e32 v74, 0xffff0000, v154
	v_lshl_add_u64 v[78:79], v[78:79], 0, v[212:213]
	v_fmac_f32_e32 v74, v2, v75
	global_store_dwordx4 v[78:79], v[82:85], off
	v_cvt_pk_bf16_f32 v74, v81, v74
	s_nop 0
	v_and_b32_e32 v81, 0xffff0000, v74
	v_lshlrev_b32_e32 v75, 16, v74
	v_mul_f32_e32 v81, v81, v81
	v_fmac_f32_e32 v81, v75, v75
	v_lshlrev_b32_e32 v75, 16, v155
	v_fmac_f32_e32 v75, v2, v76
	v_and_b32_e32 v76, 0xffff0000, v155
	v_fmac_f32_e32 v76, v2, v77
	v_cvt_pk_bf16_f32 v75, v75, v76
	v_add_f32_e32 v80, v80, v81
	v_and_b32_e32 v77, 0xffff0000, v75
	v_lshlrev_b32_e32 v76, 16, v75
	v_mul_f32_e32 v77, v77, v77
	v_fmac_f32_e32 v77, v76, v76
	v_lshlrev_b32_e32 v76, 16, v156
	v_fmac_f32_e32 v76, v2, v70
	v_and_b32_e32 v70, 0xffff0000, v156
	v_fmac_f32_e32 v70, v2, v71
	v_cvt_pk_bf16_f32 v76, v76, v70
	v_add_f32_e32 v77, v80, v77
	v_and_b32_e32 v71, 0xffff0000, v76
	v_lshlrev_b32_e32 v70, 16, v76
	v_mul_f32_e32 v71, v71, v71
	v_fmac_f32_e32 v71, v70, v70
	v_add_f32_e32 v70, v77, v71
	v_lshlrev_b32_e32 v71, 16, v157
	v_fmac_f32_e32 v71, v2, v72
	v_and_b32_e32 v72, 0xffff0000, v157
	v_fmac_f32_e32 v72, v2, v73
	v_cvt_pk_bf16_f32 v77, v71, v72
	global_store_dwordx4 v[78:79], v[74:77], off offset:256
	v_and_b32_e32 v72, 0xffff0000, v77
	v_lshlrev_b32_e32 v71, 16, v77
	v_mul_f32_e32 v72, v72, v72
	v_fmac_f32_e32 v72, v71, v71
	s_waitcnt vmcnt(15)
	v_lshlrev_b32_e32 v71, 16, v158
	v_fmac_f32_e32 v71, v2, v66
	v_and_b32_e32 v66, 0xffff0000, v158
	v_fmac_f32_e32 v66, v2, v67
	v_cvt_pk_bf16_f32 v66, v71, v66
	v_add_f32_e32 v70, v70, v72
	v_and_b32_e32 v71, 0xffff0000, v66
	v_lshlrev_b32_e32 v67, 16, v66
	v_mul_f32_e32 v71, v71, v71
	v_fmac_f32_e32 v71, v67, v67
	v_lshlrev_b32_e32 v67, 16, v159
	v_fmac_f32_e32 v67, v2, v68
	v_and_b32_e32 v68, 0xffff0000, v159
	v_fmac_f32_e32 v68, v2, v69
	v_cvt_pk_bf16_f32 v67, v67, v68
	s_nop 0
	v_and_b32_e32 v69, 0xffff0000, v67
	v_lshlrev_b32_e32 v68, 16, v67
	v_mul_f32_e32 v69, v69, v69
	v_fmac_f32_e32 v69, v68, v68
	v_lshlrev_b32_e32 v68, 16, v160
	v_fmac_f32_e32 v68, v2, v62
	v_and_b32_e32 v62, 0xffff0000, v160
	v_fmac_f32_e32 v62, v2, v63
	v_cvt_pk_bf16_f32 v68, v68, v62
	v_add_f32_e32 v69, v71, v69
	v_and_b32_e32 v63, 0xffff0000, v68
	v_lshlrev_b32_e32 v62, 16, v68
	v_mul_f32_e32 v63, v63, v63
	v_fmac_f32_e32 v63, v62, v62
	v_add_f32_e32 v62, v69, v63
	v_lshlrev_b32_e32 v63, 16, v161
	v_fmac_f32_e32 v63, v2, v64
	v_and_b32_e32 v64, 0xffff0000, v161
	v_fmac_f32_e32 v64, v2, v65
	v_cvt_pk_bf16_f32 v69, v63, v64
	s_waitcnt vmcnt(14)
	v_lshlrev_b32_e32 v65, 16, v150
	v_and_b32_e32 v64, 0xffff0000, v69
	v_lshlrev_b32_e32 v63, 16, v69
	v_mul_f32_e32 v64, v64, v64
	v_fmac_f32_e32 v64, v63, v63
	v_add_f32_e32 v64, v62, v64
	v_lshl_add_u64 v[62:63], s[84:85], 0, v[220:221]
	v_fmac_f32_e32 v65, v2, v58
	v_and_b32_e32 v58, 0xffff0000, v150
	v_lshl_add_u64 v[62:63], v[62:63], 0, v[212:213]
	v_fmac_f32_e32 v58, v2, v59
	global_store_dwordx4 v[62:63], v[66:69], off
	v_cvt_pk_bf16_f32 v58, v65, v58
	s_nop 0
	v_and_b32_e32 v65, 0xffff0000, v58
	v_lshlrev_b32_e32 v59, 16, v58
	v_mul_f32_e32 v65, v65, v65
	v_fmac_f32_e32 v65, v59, v59
	v_lshlrev_b32_e32 v59, 16, v151
	v_fmac_f32_e32 v59, v2, v60
	v_and_b32_e32 v60, 0xffff0000, v151
	v_fmac_f32_e32 v60, v2, v61
	v_cvt_pk_bf16_f32 v59, v59, v60
	v_add_f32_e32 v64, v64, v65
	v_and_b32_e32 v61, 0xffff0000, v59
	v_lshlrev_b32_e32 v60, 16, v59
	v_mul_f32_e32 v61, v61, v61
	v_fmac_f32_e32 v61, v60, v60
	v_lshlrev_b32_e32 v60, 16, v152
	v_fmac_f32_e32 v60, v2, v54
	v_and_b32_e32 v54, 0xffff0000, v152
	v_fmac_f32_e32 v54, v2, v55
	v_cvt_pk_bf16_f32 v60, v60, v54
	v_add_f32_e32 v61, v64, v61
	v_and_b32_e32 v55, 0xffff0000, v60
	v_lshlrev_b32_e32 v54, 16, v60
	v_mul_f32_e32 v55, v55, v55
	v_fmac_f32_e32 v55, v54, v54
	v_add_f32_e32 v54, v61, v55
	v_lshlrev_b32_e32 v55, 16, v153
	v_fmac_f32_e32 v55, v2, v56
	v_and_b32_e32 v56, 0xffff0000, v153
	v_fmac_f32_e32 v56, v2, v57
	v_cvt_pk_bf16_f32 v61, v55, v56
	global_store_dwordx4 v[62:63], v[58:61], off offset:256
	v_and_b32_e32 v56, 0xffff0000, v61
	v_lshlrev_b32_e32 v55, 16, v61
	v_mul_f32_e32 v56, v56, v56
	v_fmac_f32_e32 v56, v55, v55
	s_waitcnt vmcnt(15)
; __device__ __forceinline__ unsigned cvt_pk_bf16(float lo, float hi) { unsigned r; asm volatile("v_cvt_pk_bf16_f32 %0, %1, %2" : "=v"(r) : "v"(lo), "v"(hi)); return r; }
;     __device__ __forceinline__ void operator()(const f32x4 (&acc)[2][2][4][2], const Unit& u, int wr, int wc, int fr, int fq) const {
;     ...
;             for (int m = 0; m < 4; ++m) {
;                 const int row = row0 + ai * HALF + m * 16;
;                 float ss = 0.f;
; #pragma unroll
;                 for (int bj = 0; bj < 2; ++bj) {
;                     const u32x4 xo = xv[ai][m][bj]; u32x4 w;
; #pragma unroll
;                     for (int k = 0; k < 4; ++k) {
;                         const float a0 = __uint_as_float(xo[k] << 16) + acc[ai][bj][m][k >> 1][(k & 1) * 2] * scale, a1 = __uint_as_float(xo[k] & 0xffff0000u) + acc[ai][bj][m][k >> 1][(k & 1) * 2 + 1] * scale;
;                         const unsigned p = cvt_pk_bf16(a0, a1); w[k] = p;
;                         const float r0 = __uint_as_float(p << 16), r1 = __uint_as_float(p & 0xffff0000u); ss += r0 * r0 + r1 * r1;
;                     }
;                     *(u32x4*)(xb + (size_t)row * 1024 + col0 + bj * HALF) = w;
	v_lshlrev_b32_e32 v55, 16, v146
	v_fmac_f32_e32 v55, v2, v50
	v_and_b32_e32 v50, 0xffff0000, v146
	v_fmac_f32_e32 v50, v2, v51
	v_cvt_pk_bf16_f32 v50, v55, v50
	v_add_f32_e32 v54, v54, v56
	v_and_b32_e32 v55, 0xffff0000, v50
	v_lshlrev_b32_e32 v51, 16, v50
	v_mul_f32_e32 v55, v55, v55
	v_fmac_f32_e32 v55, v51, v51
	v_lshlrev_b32_e32 v51, 16, v147
	v_fmac_f32_e32 v51, v2, v52
	v_and_b32_e32 v52, 0xffff0000, v147
	v_fmac_f32_e32 v52, v2, v53
	v_cvt_pk_bf16_f32 v51, v51, v52
	s_nop 0
	v_and_b32_e32 v53, 0xffff0000, v51
	v_lshlrev_b32_e32 v52, 16, v51
	v_mul_f32_e32 v53, v53, v53
	v_fmac_f32_e32 v53, v52, v52
	v_lshlrev_b32_e32 v52, 16, v148
	v_fmac_f32_e32 v52, v2, v46
	v_and_b32_e32 v46, 0xffff0000, v148
	v_fmac_f32_e32 v46, v2, v47
	v_cvt_pk_bf16_f32 v52, v52, v46
	v_add_f32_e32 v53, v55, v53
	v_and_b32_e32 v47, 0xffff0000, v52
	v_lshlrev_b32_e32 v46, 16, v52
	v_mul_f32_e32 v47, v47, v47
	v_fmac_f32_e32 v47, v46, v46
	v_add_f32_e32 v46, v53, v47
	v_lshlrev_b32_e32 v47, 16, v149
	v_fmac_f32_e32 v47, v2, v48
	v_and_b32_e32 v48, 0xffff0000, v149
	v_fmac_f32_e32 v48, v2, v49
	v_cvt_pk_bf16_f32 v53, v47, v48
	s_waitcnt vmcnt(14)
	v_lshlrev_b32_e32 v49, 16, v142
	v_and_b32_e32 v48, 0xffff0000, v53
	v_lshlrev_b32_e32 v47, 16, v53
	v_mul_f32_e32 v48, v48, v48
	v_fmac_f32_e32 v48, v47, v47
	v_add_f32_e32 v48, v46, v48
	v_lshl_add_u64 v[46:47], s[84:85], 0, v[218:219]
	v_fmac_f32_e32 v49, v2, v42
	v_and_b32_e32 v42, 0xffff0000, v142
	v_lshl_add_u64 v[46:47], v[46:47], 0, v[212:213]
	v_fmac_f32_e32 v42, v2, v43
	global_store_dwordx4 v[46:47], v[50:53], off
	v_cvt_pk_bf16_f32 v42, v49, v42
	s_nop 0
	v_and_b32_e32 v49, 0xffff0000, v42
	v_lshlrev_b32_e32 v43, 16, v42
	v_mul_f32_e32 v49, v49, v49
	v_fmac_f32_e32 v49, v43, v43
	v_lshlrev_b32_e32 v43, 16, v143
	v_fmac_f32_e32 v43, v2, v44
	v_and_b32_e32 v44, 0xffff0000, v143
	v_fmac_f32_e32 v44, v2, v45
	v_cvt_pk_bf16_f32 v43, v43, v44
	v_add_f32_e32 v48, v48, v49
	v_and_b32_e32 v45, 0xffff0000, v43
	v_lshlrev_b32_e32 v44, 16, v43
	v_mul_f32_e32 v45, v45, v45
	v_fmac_f32_e32 v45, v44, v44
	v_lshlrev_b32_e32 v44, 16, v144
	v_fmac_f32_e32 v44, v2, v38
	v_and_b32_e32 v38, 0xffff0000, v144
	v_fmac_f32_e32 v38, v2, v39
	v_cvt_pk_bf16_f32 v44, v44, v38
	v_add_f32_e32 v45, v48, v45
	v_and_b32_e32 v39, 0xffff0000, v44
	v_lshlrev_b32_e32 v38, 16, v44
	v_mul_f32_e32 v39, v39, v39
	v_fmac_f32_e32 v39, v38, v38
	v_add_f32_e32 v38, v45, v39
	v_lshlrev_b32_e32 v39, 16, v145
	v_fmac_f32_e32 v39, v2, v40
	v_and_b32_e32 v40, 0xffff0000, v145
	v_fmac_f32_e32 v40, v2, v41
	v_cvt_pk_bf16_f32 v45, v39, v40
	global_store_dwordx4 v[46:47], v[42:45], off offset:256
	v_and_b32_e32 v40, 0xffff0000, v45
	v_lshlrev_b32_e32 v39, 16, v45
	v_mul_f32_e32 v40, v40, v40
	v_fmac_f32_e32 v40, v39, v39
	s_waitcnt vmcnt(15)
	v_lshlrev_b32_e32 v39, 16, v138
	v_fmac_f32_e32 v39, v2, v34
	v_and_b32_e32 v34, 0xffff0000, v138
	v_fmac_f32_e32 v34, v2, v35
	v_cvt_pk_bf16_f32 v34, v39, v34
	v_add_f32_e32 v38, v38, v40
	v_and_b32_e32 v39, 0xffff0000, v34
	v_lshlrev_b32_e32 v35, 16, v34
	v_mul_f32_e32 v39, v39, v39
	v_fmac_f32_e32 v39, v35, v35
	v_lshlrev_b32_e32 v35, 16, v139
	v_fmac_f32_e32 v35, v2, v36
	v_and_b32_e32 v36, 0xffff0000, v139
	v_fmac_f32_e32 v36, v2, v37
	v_cvt_pk_bf16_f32 v35, v35, v36
	s_nop 0
	v_and_b32_e32 v37, 0xffff0000, v35
	v_lshlrev_b32_e32 v36, 16, v35
	v_mul_f32_e32 v37, v37, v37
	v_fmac_f32_e32 v37, v36, v36
	v_lshlrev_b32_e32 v36, 16, v140
	v_fmac_f32_e32 v36, v2, v30
	v_and_b32_e32 v30, 0xffff0000, v140
	v_fmac_f32_e32 v30, v2, v31
	v_cvt_pk_bf16_f32 v36, v36, v30
	v_add_f32_e32 v37, v39, v37
	v_and_b32_e32 v31, 0xffff0000, v36
	v_lshlrev_b32_e32 v30, 16, v36
	v_mul_f32_e32 v31, v31, v31
	v_fmac_f32_e32 v31, v30, v30
	v_add_f32_e32 v30, v37, v31
	v_lshlrev_b32_e32 v31, 16, v141
	v_fmac_f32_e32 v31, v2, v32
	v_and_b32_e32 v32, 0xffff0000, v141
	v_fmac_f32_e32 v32, v2, v33
	v_cvt_pk_bf16_f32 v37, v31, v32
	s_waitcnt vmcnt(14)
	v_lshlrev_b32_e32 v33, 16, v134
	v_and_b32_e32 v32, 0xffff0000, v37
	v_lshlrev_b32_e32 v31, 16, v37
	v_mul_f32_e32 v32, v32, v32
	v_fmac_f32_e32 v32, v31, v31
	v_add_f32_e32 v32, v30, v32
	v_lshl_add_u64 v[30:31], s[84:85], 0, v[216:217]
	v_fmac_f32_e32 v33, v2, v26
	v_and_b32_e32 v26, 0xffff0000, v134
	v_lshl_add_u64 v[30:31], v[30:31], 0, v[212:213]
	v_fmac_f32_e32 v26, v2, v27
	global_store_dwordx4 v[30:31], v[34:37], off
	v_cvt_pk_bf16_f32 v26, v33, v26
	s_nop 0
	v_and_b32_e32 v33, 0xffff0000, v26
	v_lshlrev_b32_e32 v27, 16, v26
	v_mul_f32_e32 v33, v33, v33
	v_fmac_f32_e32 v33, v27, v27
	v_lshlrev_b32_e32 v27, 16, v135
	v_fmac_f32_e32 v27, v2, v28
	v_and_b32_e32 v28, 0xffff0000, v135
	v_fmac_f32_e32 v28, v2, v29
	v_cvt_pk_bf16_f32 v27, v27, v28
	v_add_f32_e32 v32, v32, v33
	v_and_b32_e32 v29, 0xffff0000, v27
	v_lshlrev_b32_e32 v28, 16, v27
	v_mul_f32_e32 v29, v29, v29
	v_fmac_f32_e32 v29, v28, v28
	v_lshlrev_b32_e32 v28, 16, v136
	v_fmac_f32_e32 v28, v2, v22
	v_and_b32_e32 v22, 0xffff0000, v136
	v_fmac_f32_e32 v22, v2, v23
	v_cvt_pk_bf16_f32 v28, v28, v22
	v_add_f32_e32 v29, v32, v29
	v_and_b32_e32 v23, 0xffff0000, v28
	v_lshlrev_b32_e32 v22, 16, v28
	v_mul_f32_e32 v23, v23, v23
	v_fmac_f32_e32 v23, v22, v22
	v_add_f32_e32 v22, v29, v23
	v_lshlrev_b32_e32 v23, 16, v137
	v_fmac_f32_e32 v23, v2, v24
	v_and_b32_e32 v24, 0xffff0000, v137
	v_fmac_f32_e32 v24, v2, v25
	v_cvt_pk_bf16_f32 v29, v23, v24
	global_store_dwordx4 v[30:31], v[26:29], off offset:256
	v_and_b32_e32 v24, 0xffff0000, v29
	v_lshlrev_b32_e32 v23, 16, v29
	v_mul_f32_e32 v24, v24, v24
	v_fmac_f32_e32 v24, v23, v23
	s_waitcnt vmcnt(15)
; __device__ __forceinline__ unsigned cvt_pk_bf16(float lo, float hi) { unsigned r; asm volatile("v_cvt_pk_bf16_f32 %0, %1, %2" : "=v"(r) : "v"(lo), "v"(hi)); return r; }
;     __device__ __forceinline__ void operator()(const f32x4 (&acc)[2][2][4][2], const Unit& u, int wr, int wc, int fr, int fq) const {
;     ...
;             for (int m = 0; m < 4; ++m) {
;                 const int row = row0 + ai * HALF + m * 16;
;                 float ss = 0.f;
; #pragma unroll
;                 for (int bj = 0; bj < 2; ++bj) {
;                     const u32x4 xo = xv[ai][m][bj]; u32x4 w;
; #pragma unroll
;                     for (int k = 0; k < 4; ++k) {
;                         const float a0 = __uint_as_float(xo[k] << 16) + acc[ai][bj][m][k >> 1][(k & 1) * 2] * scale, a1 = __uint_as_float(xo[k] & 0xffff0000u) + acc[ai][bj][m][k >> 1][(k & 1) * 2 + 1] * scale;
;                         const unsigned p = cvt_pk_bf16(a0, a1); w[k] = p;
;                         const float r0 = __uint_as_float(p << 16), r1 = __uint_as_float(p & 0xffff0000u); ss += r0 * r0 + r1 * r1;
;                     }
;                     *(u32x4*)(xb + (size_t)row * 1024 + col0 + bj * HALF) = w;
;                 }
;                 ssv[ai][m] = ss;
;             }
; #pragma unroll
;         for (int ai = 0; ai < 2; ++ai)
; #pragma unroll
;             for (int m = 0; m < 4; ++m) ssv[ai][m] += __shfl_xor(ssv[ai][m], 16);
; #pragma unroll
;         for (int ai = 0; ai < 2; ++ai)
; #pragma unroll
;             for (int m = 0; m < 4; ++m) ssv[ai][m] += __shfl_xor(ssv[ai][m], 32);
;         if (fq == 0 && fin) {
; #pragma unroll
;             for (int ai = 0; ai < 2; ++ai)
; #pragma unroll
;                 for (int m = 0; m < 4; ++m) unsafeAtomicAdd(rowss + row0 + ai * HALF + m * 16, ssv[ai][m]);
	v_lshlrev_b32_e32 v23, 16, v130
	v_fmac_f32_e32 v23, v2, v18
	v_and_b32_e32 v18, 0xffff0000, v130
	v_fmac_f32_e32 v18, v2, v19
	v_cvt_pk_bf16_f32 v18, v23, v18
	v_add_f32_e32 v22, v22, v24
	v_and_b32_e32 v23, 0xffff0000, v18
	v_lshlrev_b32_e32 v19, 16, v18
	v_mul_f32_e32 v23, v23, v23
	v_fmac_f32_e32 v23, v19, v19
	v_lshlrev_b32_e32 v19, 16, v131
	v_fmac_f32_e32 v19, v2, v20
	v_and_b32_e32 v20, 0xffff0000, v131
	v_fmac_f32_e32 v20, v2, v21
	v_cvt_pk_bf16_f32 v19, v19, v20
	s_nop 0
	v_and_b32_e32 v21, 0xffff0000, v19
	v_lshlrev_b32_e32 v20, 16, v19
	v_mul_f32_e32 v21, v21, v21
	v_fmac_f32_e32 v21, v20, v20
	v_lshlrev_b32_e32 v20, 16, v132
	v_fmac_f32_e32 v20, v2, v14
	v_and_b32_e32 v14, 0xffff0000, v132
	v_fmac_f32_e32 v14, v2, v15
	v_cvt_pk_bf16_f32 v20, v20, v14
	v_add_f32_e32 v21, v23, v21
	v_and_b32_e32 v15, 0xffff0000, v20
	v_lshlrev_b32_e32 v14, 16, v20
	v_mul_f32_e32 v15, v15, v15
	v_fmac_f32_e32 v15, v14, v14
	v_add_f32_e32 v14, v21, v15
	v_lshlrev_b32_e32 v15, 16, v133
	v_fmac_f32_e32 v15, v2, v16
	v_and_b32_e32 v16, 0xffff0000, v133
	v_fmac_f32_e32 v16, v2, v17
	v_cvt_pk_bf16_f32 v21, v15, v16
	s_waitcnt vmcnt(14)
	v_lshlrev_b32_e32 v17, 16, v126
	v_and_b32_e32 v16, 0xffff0000, v21
	v_lshlrev_b32_e32 v15, 16, v21
	v_mul_f32_e32 v16, v16, v16
	v_fmac_f32_e32 v16, v15, v15
	v_add_f32_e32 v16, v14, v16
	v_lshl_add_u64 v[14:15], s[84:85], 0, v[214:215]
	v_fmac_f32_e32 v17, v2, v10
	v_and_b32_e32 v10, 0xffff0000, v126
	v_lshl_add_u64 v[14:15], v[14:15], 0, v[212:213]
	v_fmac_f32_e32 v10, v2, v11
	global_store_dwordx4 v[14:15], v[18:21], off
	v_cvt_pk_bf16_f32 v10, v17, v10
	s_nop 0
	v_and_b32_e32 v17, 0xffff0000, v10
	v_lshlrev_b32_e32 v11, 16, v10
	v_mul_f32_e32 v17, v17, v17
	v_fmac_f32_e32 v17, v11, v11
	v_lshlrev_b32_e32 v11, 16, v127
	v_fmac_f32_e32 v11, v2, v12
	v_and_b32_e32 v12, 0xffff0000, v127
	v_fmac_f32_e32 v12, v2, v13
	v_cvt_pk_bf16_f32 v11, v11, v12
	v_add_f32_e32 v16, v16, v17
	v_and_b32_e32 v13, 0xffff0000, v11
	v_lshlrev_b32_e32 v12, 16, v11
	v_mul_f32_e32 v13, v13, v13
	v_fmac_f32_e32 v13, v12, v12
	v_lshlrev_b32_e32 v12, 16, v128
	v_fmac_f32_e32 v12, v2, v6
	v_and_b32_e32 v6, 0xffff0000, v128
	v_fmac_f32_e32 v6, v2, v7
	v_cvt_pk_bf16_f32 v12, v12, v6
	v_add_f32_e32 v13, v16, v13
	v_and_b32_e32 v7, 0xffff0000, v12
	v_lshlrev_b32_e32 v6, 16, v12
	v_mul_f32_e32 v7, v7, v7
	v_fmac_f32_e32 v7, v6, v6
	v_add_f32_e32 v6, v13, v7
	v_lshlrev_b32_e32 v7, 16, v129
	v_fmac_f32_e32 v7, v2, v8
	v_and_b32_e32 v8, 0xffff0000, v129
	v_fmac_f32_e32 v8, v2, v9
	v_cvt_pk_bf16_f32 v13, v7, v8
	global_store_dwordx4 v[14:15], v[10:13], off offset:256
	v_and_b32_e32 v8, 0xffff0000, v13
	v_lshlrev_b32_e32 v7, 16, v13
	v_mul_f32_e32 v8, v8, v8
	v_fmac_f32_e32 v8, v7, v7
	v_and_b32_e32 v7, 64, v232
	v_add_f32_e32 v16, v6, v8
	v_xor_b32_e32 v6, 16, v232
	v_add_u32_e32 v13, 64, v7
	v_cmp_lt_i32_e32 vcc, v6, v13
	v_xor_b32_e32 v15, 32, v232
	s_nop 0
	v_cndmask_b32_e32 v6, v232, v6, vcc
	v_lshlrev_b32_e32 v14, 2, v6
	ds_bpermute_b32 v6, v14, v118
	ds_bpermute_b32 v7, v14, v102
	ds_bpermute_b32 v8, v14, v86
	ds_bpermute_b32 v9, v14, v70
	ds_bpermute_b32 v10, v14, v54
	ds_bpermute_b32 v11, v14, v38
	ds_bpermute_b32 v12, v14, v22
	ds_bpermute_b32 v14, v14, v16
	v_cmp_lt_i32_e32 vcc, v15, v13
	s_waitcnt lgkmcnt(7)
	v_add_f32_e32 v6, v118, v6
	s_waitcnt lgkmcnt(6)
	v_add_f32_e32 v7, v102, v7
	v_cndmask_b32_e32 v13, v232, v15, vcc
	s_waitcnt lgkmcnt(5)
	v_add_f32_e32 v8, v86, v8
	s_waitcnt lgkmcnt(4)
	v_add_f32_e32 v9, v70, v9
	s_waitcnt lgkmcnt(3)
	v_add_f32_e32 v10, v54, v10
	s_waitcnt lgkmcnt(2)
	v_add_f32_e32 v11, v38, v11
	s_waitcnt lgkmcnt(1)
	v_add_f32_e32 v12, v22, v12
	s_waitcnt lgkmcnt(0)
	v_add_f32_e32 v14, v16, v14
	v_lshlrev_b32_e32 v21, 2, v13
	ds_bpermute_b32 v13, v21, v6
	ds_bpermute_b32 v15, v21, v7
	ds_bpermute_b32 v16, v21, v8
	ds_bpermute_b32 v17, v21, v9
	ds_bpermute_b32 v18, v21, v10
	ds_bpermute_b32 v19, v21, v11
	ds_bpermute_b32 v20, v21, v12
	ds_bpermute_b32 v21, v21, v14
	s_and_saveexec_b64 s[10:11], s[38:39]
	s_movk_i32 s55, 0x1a00
	s_cbranch_execz .LBB0_182
	s_waitcnt lgkmcnt(6)
	v_add_f32_e32 v15, v7, v15
	v_add_f32_e32 v13, v6, v13
	v_lshl_add_u64 v[6:7], v[210:211], 2, s[8:9]
	s_waitcnt lgkmcnt(0)
	v_add_f32_e32 v14, v14, v21
	v_add_f32_e32 v12, v12, v20
	v_add_f32_e32 v11, v11, v19
	v_add_f32_e32 v10, v10, v18
	v_add_f32_e32 v9, v9, v17
	v_add_f32_e32 v8, v8, v16
	global_atomic_add_f32 v[6:7], v13, off
	global_atomic_add_f32 v[6:7], v15, off offset:64
	global_atomic_add_f32 v[6:7], v8, off offset:128
	global_atomic_add_f32 v[6:7], v9, off offset:192
	global_atomic_add_f32 v[6:7], v10, off offset:512
	global_atomic_add_f32 v[6:7], v11, off offset:576
	global_atomic_add_f32 v[6:7], v12, off offset:640
	global_atomic_add_f32 v[6:7], v14, off offset:704
